# st9 + write-through (sc1) stores for all P0 outputs (less dirty L2 data at the first grid barrier)
# speedup vs baseline: 1.0074x; 1.0074x over previous
.LBB0_11:
	v_lshl_add_u64 v[54:55], v[32:33], 0, s[10:11]
	v_lshl_add_u64 v[56:57], v[30:31], 0, s[10:11]
	v_lshl_add_u64 v[58:59], v[28:29], 0, s[10:11]
	v_lshl_add_u64 v[60:61], v[26:27], 0, s[10:11]
	v_lshl_add_u64 v[62:63], v[24:25], 0, s[10:11]
	v_lshl_add_u64 v[64:65], v[22:23], 0, s[10:11]
	v_lshl_add_u64 v[66:67], v[16:17], 0, s[10:11]
	v_lshl_add_u64 v[68:69], v[14:15], 0, s[10:11]
	global_load_dword v166, v[54:55], off nt
	global_load_dword v167, v[56:57], off nt
	global_load_dword v168, v[58:59], off nt
	global_load_dword v169, v[60:61], off nt
	global_load_dword v170, v[62:63], off nt
	global_load_dword v171, v[64:65], off nt
	global_load_dword v172, v[66:67], off nt
	global_load_dword v173, v[68:69], off nt
	s_add_u32 s10, s10, 0x10000
	s_addc_u32 s11, s11, 0
	v_lshl_add_u64 v[54:55], v[32:33], 0, s[10:11]
	v_lshl_add_u64 v[56:57], v[30:31], 0, s[10:11]
	v_lshl_add_u64 v[58:59], v[28:29], 0, s[10:11]
	v_lshl_add_u64 v[60:61], v[26:27], 0, s[10:11]
	v_lshl_add_u64 v[62:63], v[24:25], 0, s[10:11]
	v_lshl_add_u64 v[64:65], v[22:23], 0, s[10:11]
	v_lshl_add_u64 v[66:67], v[16:17], 0, s[10:11]
	v_lshl_add_u64 v[68:69], v[14:15], 0, s[10:11]
	global_load_dword v174, v[54:55], off nt
	global_load_dword v175, v[56:57], off nt
	global_load_dword v176, v[58:59], off nt
	global_load_dword v177, v[60:61], off nt
	global_load_dword v178, v[62:63], off nt
	global_load_dword v179, v[64:65], off nt
	global_load_dword v180, v[66:67], off nt
	global_load_dword v181, v[68:69], off nt
	s_add_u32 s10, s10, 0x10000
	s_addc_u32 s11, s11, 0
	v_lshl_add_u64 v[54:55], v[32:33], 0, s[10:11]
	v_lshl_add_u64 v[56:57], v[30:31], 0, s[10:11]
	v_lshl_add_u64 v[58:59], v[28:29], 0, s[10:11]
	v_lshl_add_u64 v[60:61], v[26:27], 0, s[10:11]
	v_lshl_add_u64 v[62:63], v[24:25], 0, s[10:11]
	v_lshl_add_u64 v[64:65], v[22:23], 0, s[10:11]
	v_lshl_add_u64 v[66:67], v[16:17], 0, s[10:11]
	v_lshl_add_u64 v[68:69], v[14:15], 0, s[10:11]
	global_load_dword v182, v[54:55], off nt
	global_load_dword v183, v[56:57], off nt
	global_load_dword v184, v[58:59], off nt
	global_load_dword v185, v[60:61], off nt
	global_load_dword v186, v[62:63], off nt
	global_load_dword v248, v[64:65], off nt
	global_load_dword v249, v[66:67], off nt
	global_load_dword v250, v[68:69], off nt
	s_add_u32 s10, s10, 0x10000
	s_addc_u32 s11, s11, 0
	v_lshl_add_u64 v[54:55], v[32:33], 0, s[10:11]
	v_lshl_add_u64 v[56:57], v[30:31], 0, s[10:11]
	v_lshl_add_u64 v[58:59], v[28:29], 0, s[10:11]
	v_lshl_add_u64 v[60:61], v[26:27], 0, s[10:11]
	v_lshl_add_u64 v[62:63], v[24:25], 0, s[10:11]
	v_lshl_add_u64 v[64:65], v[22:23], 0, s[10:11]
	v_lshl_add_u64 v[66:67], v[16:17], 0, s[10:11]
	v_lshl_add_u64 v[68:69], v[14:15], 0, s[10:11]
	global_load_dword v251, v[54:55], off nt
	global_load_dword v252, v[56:57], off nt
	global_load_dword v253, v[58:59], off nt
	global_load_dword v254, v[60:61], off nt
	global_load_dword v255, v[62:63], off nt
	global_load_dword v187, v[64:65], off nt
	global_load_dword v188, v[66:67], off nt
	global_load_dword v189, v[68:69], off nt
	s_add_u32 s10, s10, 0x10000
	s_addc_u32 s11, s11, 0
	v_add_u32_e32 v61, 0x400, v2
	s_waitcnt vmcnt(30)
	ds_write2_b32 v2, v166, v167 offset1:66
	s_waitcnt vmcnt(28)
	ds_write2_b32 v2, v168, v169 offset0:132 offset1:198
	s_waitcnt vmcnt(26)
	ds_write2_b32 v61, v170, v171 offset0:8 offset1:74
	s_waitcnt vmcnt(24)
	ds_write2_b32 v61, v172, v173 offset0:140 offset1:206
	v_add_u32_e32 v2, 0x840, v2
	v_add_u32_e32 v61, 0x400, v2
	s_waitcnt vmcnt(22)
	ds_write2_b32 v2, v174, v175 offset1:66
	s_waitcnt vmcnt(20)
	ds_write2_b32 v2, v176, v177 offset0:132 offset1:198
	s_waitcnt vmcnt(18)
	ds_write2_b32 v61, v178, v179 offset0:8 offset1:74
	s_waitcnt vmcnt(16)
	ds_write2_b32 v61, v180, v181 offset0:140 offset1:206
	v_add_u32_e32 v2, 0x840, v2
	v_add_u32_e32 v61, 0x400, v2
	s_waitcnt vmcnt(14)
	ds_write2_b32 v2, v182, v183 offset1:66
	s_waitcnt vmcnt(12)
	ds_write2_b32 v2, v184, v185 offset0:132 offset1:198
	s_waitcnt vmcnt(10)
	ds_write2_b32 v61, v186, v248 offset0:8 offset1:74
	s_waitcnt vmcnt(8)
	ds_write2_b32 v61, v249, v250 offset0:140 offset1:206
	v_add_u32_e32 v2, 0x840, v2
	v_add_u32_e32 v61, 0x400, v2
	s_waitcnt vmcnt(6)
	ds_write2_b32 v2, v251, v252 offset1:66
	s_waitcnt vmcnt(4)
	ds_write2_b32 v2, v253, v254 offset0:132 offset1:198
	s_waitcnt vmcnt(2)
	ds_write2_b32 v61, v255, v187 offset0:8 offset1:74
	s_waitcnt vmcnt(0)
	ds_write2_b32 v61, v188, v189 offset0:140 offset1:206
	v_add_u32_e32 v2, 0x840, v2
	v_lshl_add_u32 v2, v51, 1, v49
	s_waitcnt lgkmcnt(0)
	v_and_b32_e32 v2, 0x1ffc0, v2
	v_and_b32_e32 v60, 0x3e0, v52
	ds_read2_b32 v[22:23], v34 offset0:33 offset1:41
	ds_read2_b32 v[24:25], v34 offset1:8
	ds_read2_b32 v[26:27], v34 offset0:66 offset1:74
	ds_read2_b32 v[28:29], v34 offset0:99 offset1:107
	ds_read2_b32 v[30:31], v34 offset0:132 offset1:140
	ds_read2_b32 v[32:33], v34 offset0:165 offset1:173
	ds_read2_b32 v[52:53], v34 offset0:198 offset1:206
	ds_read2_b32 v[54:55], v34 offset0:231 offset1:239
	v_lshlrev_b32_e32 v2, 1, v2
	v_lshl_add_u64 v[56:57], v[4:5], 0, v[2:3]
	v_or_b32_e32 v2, v60, v21
	v_lshlrev_b32_e32 v2, 11, v2
	v_lshl_add_u64 v[58:59], v[56:57], 0, v[2:3]
	s_waitcnt lgkmcnt(6)
	v_cvt_pk_bf16_f32 v14, v24, v22
	s_waitcnt lgkmcnt(4)
	v_cvt_pk_bf16_f32 v15, v26, v28
	s_waitcnt lgkmcnt(2)
	v_cvt_pk_bf16_f32 v16, v30, v32
	s_waitcnt lgkmcnt(0)
	v_cvt_pk_bf16_f32 v17, v52, v54
	global_store_dwordx4 v[58:59], v[14:17], off sc1
	v_or_b32_e32 v2, v60, v35
	v_lshlrev_b32_e32 v2, 11, v2
	v_cvt_pk_bf16_f32 v14, v25, v23
	v_cvt_pk_bf16_f32 v15, v27, v29
	v_cvt_pk_bf16_f32 v16, v31, v33
	v_cvt_pk_bf16_f32 v17, v53, v55
	ds_read2_b32 v[24:25], v34 offset0:16 offset1:24
	ds_read2_b32 v[26:27], v34 offset0:49 offset1:57
	ds_read2_b32 v[28:29], v34 offset0:82 offset1:90
	ds_read2_b32 v[30:31], v34 offset0:115 offset1:123
	ds_read2_b32 v[32:33], v34 offset0:148 offset1:156
	ds_read2_b32 v[52:53], v34 offset0:181 offset1:189
	ds_read2_b32 v[54:55], v34 offset0:214 offset1:222
	ds_read2_b32 v[58:59], v34 offset0:247 offset1:255
	v_lshl_add_u64 v[22:23], v[56:57], 0, v[2:3]
	v_or_b32_e32 v2, v60, v36
	v_lshlrev_b32_e32 v2, 11, v2
	global_store_dwordx4 v[22:23], v[14:17], off sc1
	v_lshl_add_u64 v[22:23], v[56:57], 0, v[2:3]
	v_or_b32_e32 v2, v60, v37
	v_lshlrev_b32_e32 v2, 11, v2
	s_waitcnt lgkmcnt(6)
	v_cvt_pk_bf16_f32 v14, v24, v26
	s_waitcnt lgkmcnt(4)
	v_cvt_pk_bf16_f32 v15, v28, v30
	s_waitcnt lgkmcnt(2)
	v_cvt_pk_bf16_f32 v16, v32, v52
	s_waitcnt lgkmcnt(0)
	v_cvt_pk_bf16_f32 v17, v54, v58
	global_store_dwordx4 v[22:23], v[14:17], off sc1
	v_lshl_add_u64 v[22:23], v[56:57], 0, v[2:3]
	s_nop 0
	v_cvt_pk_bf16_f32 v14, v25, v27
	v_cvt_pk_bf16_f32 v15, v29, v31
	v_cvt_pk_bf16_f32 v16, v33, v53
	v_cvt_pk_bf16_f32 v17, v55, v59
	global_store_dwordx4 v[22:23], v[14:17], off sc1
	s_waitcnt lgkmcnt(0)

.LBB0_15:
	v_lshl_add_u64 v[54:55], v[32:33], 0, s[10:11]
	v_lshl_add_u64 v[56:57], v[30:31], 0, s[10:11]
	v_lshl_add_u64 v[58:59], v[28:29], 0, s[10:11]
	v_lshl_add_u64 v[60:61], v[26:27], 0, s[10:11]
	v_lshl_add_u64 v[62:63], v[24:25], 0, s[10:11]
	v_lshl_add_u64 v[64:65], v[22:23], 0, s[10:11]
	v_lshl_add_u64 v[66:67], v[16:17], 0, s[10:11]
	v_lshl_add_u64 v[68:69], v[14:15], 0, s[10:11]
	global_load_dword v166, v[54:55], off nt
	global_load_dword v167, v[56:57], off nt
	global_load_dword v168, v[58:59], off nt
	global_load_dword v169, v[60:61], off nt
	global_load_dword v170, v[62:63], off nt
	global_load_dword v171, v[64:65], off nt
	global_load_dword v172, v[66:67], off nt
	global_load_dword v173, v[68:69], off nt
	s_add_u32 s10, s10, 0x8000
	s_addc_u32 s11, s11, 0
	v_lshl_add_u64 v[54:55], v[32:33], 0, s[10:11]
	v_lshl_add_u64 v[56:57], v[30:31], 0, s[10:11]
	v_lshl_add_u64 v[58:59], v[28:29], 0, s[10:11]
	v_lshl_add_u64 v[60:61], v[26:27], 0, s[10:11]
	v_lshl_add_u64 v[62:63], v[24:25], 0, s[10:11]
	v_lshl_add_u64 v[64:65], v[22:23], 0, s[10:11]
	v_lshl_add_u64 v[66:67], v[16:17], 0, s[10:11]
	v_lshl_add_u64 v[68:69], v[14:15], 0, s[10:11]
	global_load_dword v174, v[54:55], off nt
	global_load_dword v175, v[56:57], off nt
	global_load_dword v176, v[58:59], off nt
	global_load_dword v177, v[60:61], off nt
	global_load_dword v178, v[62:63], off nt
	global_load_dword v179, v[64:65], off nt
	global_load_dword v180, v[66:67], off nt
	global_load_dword v181, v[68:69], off nt
	s_add_u32 s10, s10, 0x8000
	s_addc_u32 s11, s11, 0
	v_lshl_add_u64 v[54:55], v[32:33], 0, s[10:11]
	v_lshl_add_u64 v[56:57], v[30:31], 0, s[10:11]
	v_lshl_add_u64 v[58:59], v[28:29], 0, s[10:11]
	v_lshl_add_u64 v[60:61], v[26:27], 0, s[10:11]
	v_lshl_add_u64 v[62:63], v[24:25], 0, s[10:11]
	v_lshl_add_u64 v[64:65], v[22:23], 0, s[10:11]
	v_lshl_add_u64 v[66:67], v[16:17], 0, s[10:11]
	v_lshl_add_u64 v[68:69], v[14:15], 0, s[10:11]
	global_load_dword v182, v[54:55], off nt
	global_load_dword v183, v[56:57], off nt
	global_load_dword v184, v[58:59], off nt
	global_load_dword v185, v[60:61], off nt
	global_load_dword v186, v[62:63], off nt
	global_load_dword v248, v[64:65], off nt
	global_load_dword v249, v[66:67], off nt
	global_load_dword v250, v[68:69], off nt
	s_add_u32 s10, s10, 0x8000
	s_addc_u32 s11, s11, 0
	v_lshl_add_u64 v[54:55], v[32:33], 0, s[10:11]
	v_lshl_add_u64 v[56:57], v[30:31], 0, s[10:11]
	v_lshl_add_u64 v[58:59], v[28:29], 0, s[10:11]
	v_lshl_add_u64 v[60:61], v[26:27], 0, s[10:11]
	v_lshl_add_u64 v[62:63], v[24:25], 0, s[10:11]
	v_lshl_add_u64 v[64:65], v[22:23], 0, s[10:11]
	v_lshl_add_u64 v[66:67], v[16:17], 0, s[10:11]
	v_lshl_add_u64 v[68:69], v[14:15], 0, s[10:11]
	global_load_dword v251, v[54:55], off nt
	global_load_dword v252, v[56:57], off nt
	global_load_dword v253, v[58:59], off nt
	global_load_dword v254, v[60:61], off nt
	global_load_dword v255, v[62:63], off nt
	global_load_dword v187, v[64:65], off nt
	global_load_dword v188, v[66:67], off nt
	global_load_dword v189, v[68:69], off nt
	s_add_u32 s10, s10, 0x8000
	s_addc_u32 s11, s11, 0
	v_add_u32_e32 v62, 0x400, v2
	s_waitcnt vmcnt(30)
	ds_write2_b32 v2, v166, v167 offset1:66
	s_waitcnt vmcnt(28)
	ds_write2_b32 v2, v168, v169 offset0:132 offset1:198
	s_waitcnt vmcnt(26)
	ds_write2_b32 v62, v170, v171 offset0:8 offset1:74
	s_waitcnt vmcnt(24)
	ds_write2_b32 v62, v172, v173 offset0:140 offset1:206
	v_add_u32_e32 v2, 0x840, v2
	v_add_u32_e32 v62, 0x400, v2
	s_waitcnt vmcnt(22)
	ds_write2_b32 v2, v174, v175 offset1:66
	s_waitcnt vmcnt(20)
	ds_write2_b32 v2, v176, v177 offset0:132 offset1:198
	s_waitcnt vmcnt(18)
	ds_write2_b32 v62, v178, v179 offset0:8 offset1:74
	s_waitcnt vmcnt(16)
	ds_write2_b32 v62, v180, v181 offset0:140 offset1:206
	v_add_u32_e32 v2, 0x840, v2
	v_add_u32_e32 v62, 0x400, v2
	s_waitcnt vmcnt(14)
	ds_write2_b32 v2, v182, v183 offset1:66
	s_waitcnt vmcnt(12)
	ds_write2_b32 v2, v184, v185 offset0:132 offset1:198
	s_waitcnt vmcnt(10)
	ds_write2_b32 v62, v186, v248 offset0:8 offset1:74
	s_waitcnt vmcnt(8)
	ds_write2_b32 v62, v249, v250 offset0:140 offset1:206
	v_add_u32_e32 v2, 0x840, v2
	v_add_u32_e32 v62, 0x400, v2
	s_waitcnt vmcnt(6)
	ds_write2_b32 v2, v251, v252 offset1:66
	s_waitcnt vmcnt(4)
	ds_write2_b32 v2, v253, v254 offset0:132 offset1:198
	s_waitcnt vmcnt(2)
	ds_write2_b32 v62, v255, v187 offset0:8 offset1:74
	s_waitcnt vmcnt(0)
	ds_write2_b32 v62, v188, v189 offset0:140 offset1:206
	v_add_u32_e32 v2, 0x840, v2
	v_and_b32_e32 v2, 0x1e0, v52
	s_waitcnt lgkmcnt(0)
	v_add_u32_e32 v60, 0x900, v2
	v_lshlrev_b32_e32 v2, 1, v53
	ds_read2_b32 v[22:23], v34 offset0:33 offset1:41
	ds_read2_b32 v[24:25], v34 offset1:8
	ds_read2_b32 v[26:27], v34 offset0:66 offset1:74
	ds_read2_b32 v[28:29], v34 offset0:99 offset1:107
	ds_read2_b32 v[30:31], v34 offset0:132 offset1:140
	ds_read2_b32 v[32:33], v34 offset0:165 offset1:173
	ds_read2_b32 v[52:53], v34 offset0:198 offset1:206
	ds_read2_b32 v[54:55], v34 offset0:231 offset1:239
	v_lshl_add_u64 v[56:57], v[6:7], 0, v[2:3]
	v_or_b32_e32 v2, v60, v21
	v_lshlrev_b32_e32 v2, 11, v2
	v_lshl_add_u64 v[58:59], v[56:57], 0, v[2:3]
	s_waitcnt lgkmcnt(6)
	v_cvt_pk_bf16_f32 v14, v24, v22
	s_waitcnt lgkmcnt(4)
	v_cvt_pk_bf16_f32 v15, v26, v28
	s_waitcnt lgkmcnt(2)
	v_cvt_pk_bf16_f32 v16, v30, v32
	s_waitcnt lgkmcnt(0)
	v_cvt_pk_bf16_f32 v17, v52, v54
	global_store_dwordx4 v[58:59], v[14:17], off sc1
	v_or_b32_e32 v2, v60, v35
	v_lshlrev_b32_e32 v2, 11, v2
	v_cvt_pk_bf16_f32 v14, v25, v23
	v_cvt_pk_bf16_f32 v15, v27, v29
	v_cvt_pk_bf16_f32 v16, v31, v33
	v_cvt_pk_bf16_f32 v17, v53, v55
	ds_read2_b32 v[24:25], v34 offset0:16 offset1:24
	ds_read2_b32 v[26:27], v34 offset0:49 offset1:57
	ds_read2_b32 v[28:29], v34 offset0:82 offset1:90
	ds_read2_b32 v[30:31], v34 offset0:115 offset1:123
	ds_read2_b32 v[32:33], v34 offset0:148 offset1:156
	ds_read2_b32 v[52:53], v34 offset0:181 offset1:189
	ds_read2_b32 v[54:55], v34 offset0:214 offset1:222
	ds_read2_b32 v[58:59], v34 offset0:247 offset1:255
	v_lshl_add_u64 v[22:23], v[56:57], 0, v[2:3]
	v_or_b32_e32 v2, v60, v36
	v_lshlrev_b32_e32 v2, 11, v2
	global_store_dwordx4 v[22:23], v[14:17], off sc1
	v_lshl_add_u64 v[22:23], v[56:57], 0, v[2:3]
	v_or_b32_e32 v2, v60, v37
	v_lshlrev_b32_e32 v2, 11, v2
	s_waitcnt lgkmcnt(6)
	v_cvt_pk_bf16_f32 v14, v24, v26
	s_waitcnt lgkmcnt(4)
	v_cvt_pk_bf16_f32 v15, v28, v30
	s_waitcnt lgkmcnt(2)
	v_cvt_pk_bf16_f32 v16, v32, v52
	s_waitcnt lgkmcnt(0)
	v_cvt_pk_bf16_f32 v17, v54, v58
	global_store_dwordx4 v[22:23], v[14:17], off sc1
	v_lshl_add_u64 v[22:23], v[56:57], 0, v[2:3]
	s_nop 0
	v_cvt_pk_bf16_f32 v14, v25, v27
	v_cvt_pk_bf16_f32 v15, v29, v31
	v_cvt_pk_bf16_f32 v16, v33, v53
	v_cvt_pk_bf16_f32 v17, v55, v59
	global_store_dwordx4 v[22:23], v[14:17], off sc1
	s_waitcnt lgkmcnt(0)

.LBB0_20:
	v_add_u32_e32 v17, s8, v2
	v_add_u32_e32 v26, 2, v17
	v_add_u32_e32 v28, 4, v17
	v_add_u32_e32 v30, 6, v17
	v_mad_i64_i32 v[24:25], s[10:11], v17, s18, v[22:23]
	v_add_u32_e32 v32, 8, v17
	v_add_u32_e32 v52, 10, v17
	v_add_u32_e32 v54, 12, v17
	v_add_u32_e32 v17, 14, v17
	v_mad_i64_i32 v[26:27], s[10:11], v26, s18, v[22:23]
	v_mad_i64_i32 v[28:29], s[10:11], v28, s18, v[22:23]
	v_mad_i64_i32 v[30:31], s[10:11], v30, s18, v[22:23]
	v_mad_i64_i32 v[32:33], s[10:11], v32, s18, v[22:23]
	v_mad_i64_i32 v[52:53], s[10:11], v52, s18, v[22:23]
	v_mad_i64_i32 v[54:55], s[10:11], v54, s18, v[22:23]
	v_mad_i64_i32 v[56:57], s[10:11], v17, s18, v[22:23]
	global_load_dword v166, v[24:25], off nt
	global_load_dword v167, v[26:27], off nt
	global_load_dword v168, v[28:29], off nt
	global_load_dword v169, v[30:31], off nt
	global_load_dword v170, v[32:33], off nt
	global_load_dword v171, v[52:53], off nt
	global_load_dword v172, v[54:55], off nt
	global_load_dword v173, v[56:57], off nt
	s_add_i32 s8, s8, 16
	v_add_u32_e32 v17, s8, v2
	v_add_u32_e32 v26, 2, v17
	v_add_u32_e32 v28, 4, v17
	v_add_u32_e32 v30, 6, v17
	v_mad_i64_i32 v[24:25], s[10:11], v17, s18, v[22:23]
	v_add_u32_e32 v32, 8, v17
	v_add_u32_e32 v52, 10, v17
	v_add_u32_e32 v54, 12, v17
	v_add_u32_e32 v17, 14, v17
	v_mad_i64_i32 v[26:27], s[10:11], v26, s18, v[22:23]
	v_mad_i64_i32 v[28:29], s[10:11], v28, s18, v[22:23]
	v_mad_i64_i32 v[30:31], s[10:11], v30, s18, v[22:23]
	v_mad_i64_i32 v[32:33], s[10:11], v32, s18, v[22:23]
	v_mad_i64_i32 v[52:53], s[10:11], v52, s18, v[22:23]
	v_mad_i64_i32 v[54:55], s[10:11], v54, s18, v[22:23]
	v_mad_i64_i32 v[56:57], s[10:11], v17, s18, v[22:23]
	global_load_dword v174, v[24:25], off nt
	global_load_dword v175, v[26:27], off nt
	global_load_dword v176, v[28:29], off nt
	global_load_dword v177, v[30:31], off nt
	global_load_dword v178, v[32:33], off nt
	global_load_dword v179, v[52:53], off nt
	global_load_dword v180, v[54:55], off nt
	global_load_dword v181, v[56:57], off nt
	s_add_i32 s8, s8, 16
	v_add_u32_e32 v17, s8, v2
	v_add_u32_e32 v26, 2, v17
	v_add_u32_e32 v28, 4, v17
	v_add_u32_e32 v30, 6, v17
	v_mad_i64_i32 v[24:25], s[10:11], v17, s18, v[22:23]
	v_add_u32_e32 v32, 8, v17
	v_add_u32_e32 v52, 10, v17
	v_add_u32_e32 v54, 12, v17
	v_add_u32_e32 v17, 14, v17
	v_mad_i64_i32 v[26:27], s[10:11], v26, s18, v[22:23]
	v_mad_i64_i32 v[28:29], s[10:11], v28, s18, v[22:23]
	v_mad_i64_i32 v[30:31], s[10:11], v30, s18, v[22:23]
	v_mad_i64_i32 v[32:33], s[10:11], v32, s18, v[22:23]
	v_mad_i64_i32 v[52:53], s[10:11], v52, s18, v[22:23]
	v_mad_i64_i32 v[54:55], s[10:11], v54, s18, v[22:23]
	v_mad_i64_i32 v[56:57], s[10:11], v17, s18, v[22:23]
	global_load_dword v182, v[24:25], off nt
	global_load_dword v183, v[26:27], off nt
	global_load_dword v184, v[28:29], off nt
	global_load_dword v185, v[30:31], off nt
	global_load_dword v186, v[32:33], off nt
	global_load_dword v248, v[52:53], off nt
	global_load_dword v249, v[54:55], off nt
	global_load_dword v250, v[56:57], off nt
	s_add_i32 s8, s8, 16
	v_add_u32_e32 v17, s8, v2
	v_add_u32_e32 v26, 2, v17
	v_add_u32_e32 v28, 4, v17
	v_add_u32_e32 v30, 6, v17
	v_mad_i64_i32 v[24:25], s[10:11], v17, s18, v[22:23]
	v_add_u32_e32 v32, 8, v17
	v_add_u32_e32 v52, 10, v17
	v_add_u32_e32 v54, 12, v17
	v_add_u32_e32 v17, 14, v17
	v_mad_i64_i32 v[26:27], s[10:11], v26, s18, v[22:23]
	v_mad_i64_i32 v[28:29], s[10:11], v28, s18, v[22:23]
	v_mad_i64_i32 v[30:31], s[10:11], v30, s18, v[22:23]
	v_mad_i64_i32 v[32:33], s[10:11], v32, s18, v[22:23]
	v_mad_i64_i32 v[52:53], s[10:11], v52, s18, v[22:23]
	v_mad_i64_i32 v[54:55], s[10:11], v54, s18, v[22:23]
	v_mad_i64_i32 v[56:57], s[10:11], v17, s18, v[22:23]
	global_load_dword v251, v[24:25], off nt
	global_load_dword v252, v[26:27], off nt
	global_load_dword v253, v[28:29], off nt
	global_load_dword v254, v[30:31], off nt
	global_load_dword v255, v[32:33], off nt
	global_load_dword v187, v[52:53], off nt
	global_load_dword v188, v[54:55], off nt
	global_load_dword v189, v[56:57], off nt
	s_add_i32 s8, s8, 16
	v_add_u32_e32 v31, 0x400, v15
	s_waitcnt vmcnt(30)
	ds_write2_b32 v15, v166, v167 offset1:66
	s_waitcnt vmcnt(28)
	ds_write2_b32 v15, v168, v169 offset0:132 offset1:198
	s_waitcnt vmcnt(26)
	ds_write2_b32 v31, v170, v171 offset0:8 offset1:74
	s_waitcnt vmcnt(24)
	ds_write2_b32 v31, v172, v173 offset0:140 offset1:206
	v_add_u32_e32 v15, 0x840, v15
	v_add_u32_e32 v31, 0x400, v15
	s_waitcnt vmcnt(22)
	ds_write2_b32 v15, v174, v175 offset1:66
	s_waitcnt vmcnt(20)
	ds_write2_b32 v15, v176, v177 offset0:132 offset1:198
	s_waitcnt vmcnt(18)
	ds_write2_b32 v31, v178, v179 offset0:8 offset1:74
	s_waitcnt vmcnt(16)
	ds_write2_b32 v31, v180, v181 offset0:140 offset1:206
	v_add_u32_e32 v15, 0x840, v15
	v_add_u32_e32 v31, 0x400, v15
	s_waitcnt vmcnt(14)
	ds_write2_b32 v15, v182, v183 offset1:66
	s_waitcnt vmcnt(12)
	ds_write2_b32 v15, v184, v185 offset0:132 offset1:198
	s_waitcnt vmcnt(10)
	ds_write2_b32 v31, v186, v248 offset0:8 offset1:74
	s_waitcnt vmcnt(8)
	ds_write2_b32 v31, v249, v250 offset0:140 offset1:206
	v_add_u32_e32 v15, 0x840, v15
	v_add_u32_e32 v31, 0x400, v15
	s_waitcnt vmcnt(6)
	ds_write2_b32 v15, v251, v252 offset1:66
	s_waitcnt vmcnt(4)
	ds_write2_b32 v15, v253, v254 offset0:132 offset1:198
	s_waitcnt vmcnt(2)
	ds_write2_b32 v31, v255, v187 offset0:8 offset1:74
	s_waitcnt vmcnt(0)
	ds_write2_b32 v31, v188, v189 offset0:140 offset1:206
	v_add_u32_e32 v15, 0x840, v15
	s_waitcnt lgkmcnt(0)
	ds_read2_b32 v[26:27], v34 offset0:33 offset1:41
	ds_read2_b32 v[28:29], v34 offset1:8
	ds_read2_b32 v[30:31], v34 offset0:66 offset1:74
	ds_read2_b32 v[32:33], v34 offset0:99 offset1:107
	ds_read2_b32 v[52:53], v34 offset0:132 offset1:140
	ds_read2_b32 v[54:55], v34 offset0:165 offset1:173
	ds_read2_b32 v[56:57], v34 offset0:198 offset1:206
	ds_read2_b32 v[58:59], v34 offset0:231 offset1:239
	v_or_b32_e32 v60, v14, v21
	v_ashrrev_i32_e32 v17, 31, v16
	v_ashrrev_i32_e32 v61, 31, v60
	v_lshl_add_u64 v[16:17], v[16:17], 1, v[6:7]
	v_lshlrev_b64 v[60:61], 11, v[60:61]
	s_waitcnt lgkmcnt(6)
	v_cvt_pk_bf16_f32 v22, v28, v26
	v_lshl_add_u64 v[60:61], v[16:17], 0, v[60:61]
	v_or_b32_e32 v26, v14, v35
	s_waitcnt lgkmcnt(4)
	v_cvt_pk_bf16_f32 v23, v30, v32
	s_waitcnt lgkmcnt(2)
	v_cvt_pk_bf16_f32 v24, v52, v54
	s_waitcnt lgkmcnt(0)
	v_cvt_pk_bf16_f32 v25, v56, v58
	global_store_dwordx4 v[60:61], v[22:25], off sc1
	s_nop 1
	v_cvt_pk_bf16_f32 v22, v29, v27
	v_ashrrev_i32_e32 v27, 31, v26
	v_cvt_pk_bf16_f32 v23, v31, v33
	v_cvt_pk_bf16_f32 v24, v53, v55
	v_cvt_pk_bf16_f32 v25, v57, v59
	v_lshlrev_b64 v[26:27], 11, v[26:27]
	ds_read2_b32 v[28:29], v34 offset0:16 offset1:24
	ds_read2_b32 v[30:31], v34 offset0:49 offset1:57
	ds_read2_b32 v[32:33], v34 offset0:82 offset1:90
	ds_read2_b32 v[52:53], v34 offset0:115 offset1:123
	ds_read2_b32 v[54:55], v34 offset0:148 offset1:156
	ds_read2_b32 v[56:57], v34 offset0:181 offset1:189
	ds_read2_b32 v[58:59], v34 offset0:214 offset1:222
	ds_read2_b32 v[60:61], v34 offset0:247 offset1:255
	v_lshl_add_u64 v[26:27], v[16:17], 0, v[26:27]
	global_store_dwordx4 v[26:27], v[22:25], off sc1
	v_or_b32_e32 v26, v14, v36
	v_or_b32_e32 v14, v14, v37
	v_ashrrev_i32_e32 v27, 31, v26
	v_ashrrev_i32_e32 v15, 31, v14
	v_lshlrev_b64 v[26:27], 11, v[26:27]
	v_lshlrev_b64 v[14:15], 11, v[14:15]
	s_waitcnt lgkmcnt(6)
	v_cvt_pk_bf16_f32 v22, v28, v30
	s_waitcnt lgkmcnt(4)
	v_cvt_pk_bf16_f32 v23, v32, v52
	s_waitcnt lgkmcnt(2)
	v_cvt_pk_bf16_f32 v24, v54, v56
	s_waitcnt lgkmcnt(0)
	v_cvt_pk_bf16_f32 v25, v58, v60
	v_lshl_add_u64 v[26:27], v[16:17], 0, v[26:27]
	v_lshl_add_u64 v[14:15], v[16:17], 0, v[14:15]
	global_store_dwordx4 v[26:27], v[22:25], off sc1
	s_nop 1
	v_cvt_pk_bf16_f32 v22, v29, v31
	v_cvt_pk_bf16_f32 v23, v33, v53
	v_cvt_pk_bf16_f32 v24, v55, v57
	v_cvt_pk_bf16_f32 v25, v59, v61
	global_store_dwordx4 v[14:15], v[22:25], off sc1
	s_waitcnt lgkmcnt(0)
	s_branch .LBB0_7

.LBB0_24:
	v_ashrrev_i32_e32 v33, 31, v32
	v_lshlrev_b64 v[34:35], 12, v[32:33]
	v_lshlrev_b64 v[48:49], 11, v[32:33]
	v_lshl_add_u64 v[60:61], v[26:27], 0, v[34:35]
	v_add_u32_e32 v21, s2, v32
	v_add_u32_e32 v23, s3, v32
	v_add_u32_e32 v37, s13, v32
	global_load_dwordx4 v[10:13], v[28:29], off
	global_load_dwordx4 v[2:5], v[28:29], off offset:1024
	global_load_dwordx4 v[14:17], v[28:29], off offset:2048
	global_load_dwordx4 v[6:9], v[28:29], off offset:3072
	v_lshl_add_u64 v[34:35], v[24:25], 0, v[48:49]
	global_load_dwordx4 v[48:51], v[60:61], off nt
	global_load_dwordx4 v[52:55], v[60:61], off offset:1024 nt
	global_load_dwordx4 v[56:59], v[60:61], off offset:3072 nt
	s_nop 0
	global_load_dwordx4 v[60:63], v[60:61], off offset:2048 nt
	v_min_i32_e32 v36, 0x7fff, v21
	v_min_i32_e32 v38, 0x7fff, v23
	v_min_i32_e32 v40, 0x7fff, v37
	v_ashrrev_i32_e32 v37, 31, v36
	v_ashrrev_i32_e32 v39, 31, v38
	v_ashrrev_i32_e32 v41, 31, v40
	v_lshlrev_b64 v[64:65], 12, v[36:37]
	v_lshlrev_b64 v[66:67], 12, v[38:39]
	v_lshlrev_b64 v[68:69], 12, v[40:41]
	v_lshlrev_b64 v[36:37], 11, v[36:37]
	v_lshlrev_b64 v[70:71], 11, v[40:41]
	v_lshl_add_u64 v[76:77], v[26:27], 0, v[64:65]
	v_lshl_add_u64 v[100:101], v[26:27], 0, v[66:67]
	v_lshl_add_u64 v[108:109], v[26:27], 0, v[68:69]
	v_lshl_add_u64 v[40:41], v[24:25], 0, v[36:37]
	v_lshl_add_u64 v[36:37], v[24:25], 0, v[70:71]
	global_load_dwordx4 v[64:67], v[76:77], off nt
	global_load_dwordx4 v[68:71], v[76:77], off offset:1024 nt
	global_load_dwordx4 v[72:75], v[76:77], off offset:3072 nt
	s_nop 0
	global_load_dwordx4 v[76:79], v[76:77], off offset:2048 nt
	s_nop 0
	global_load_dwordx4 v[80:83], v[100:101], off nt
	global_load_dwordx4 v[84:87], v[100:101], off offset:1024 nt
	global_load_dwordx4 v[88:91], v[108:109], off nt
	global_load_dwordx4 v[92:95], v[108:109], off offset:1024 nt
	global_load_dwordx4 v[96:99], v[100:101], off offset:2048 nt
	s_nop 0
	global_load_dwordx4 v[100:103], v[100:101], off offset:3072 nt
	s_nop 0
	global_load_dwordx4 v[104:107], v[108:109], off offset:2048 nt
	s_nop 0
	global_load_dwordx4 v[108:111], v[108:109], off offset:3072 nt
	v_add_u32_e32 v32, s16, v21
	v_cmp_lt_i32_e32 vcc, s14, v32
	s_or_b64 s[10:11], vcc, s[10:11]
	v_lshlrev_b64 v[38:39], 11, v[38:39]
	v_lshl_add_u64 v[38:39], v[24:25], 0, v[38:39]
	s_waitcnt vmcnt(15)
	v_pk_mul_f32 v[112:113], v[50:51], v[50:51]
	v_pk_mul_f32 v[114:115], v[48:49], v[48:49]
	s_waitcnt vmcnt(14)
	v_pk_mul_f32 v[116:117], v[54:55], v[54:55]
	v_pk_mul_f32 v[118:119], v[52:53], v[52:53]
	s_waitcnt vmcnt(12)
	v_mul_f32_e32 v120, v61, v61
	v_mul_f32_e32 v122, v63, v63
	v_mul_f32_e32 v21, v58, v58
	v_mul_f32_e32 v23, v59, v59
	v_pk_mov_b32 v[124:125], v[114:115], v[112:113] op_sel:[1,0]
	v_mov_b32_e32 v115, v113
	v_pk_mov_b32 v[112:113], v[118:119], v[116:117] op_sel:[1,0]
	v_mov_b32_e32 v119, v117
	v_pk_fma_f32 v[116:117], v[60:61], v[60:61], v[120:121] op_sel_hi:[1,1,0]
	v_pk_fma_f32 v[120:121], v[62:63], v[62:63], v[122:123] op_sel_hi:[1,1,0]
	v_pk_add_f32 v[114:115], v[124:125], v[114:115]
	v_pk_add_f32 v[112:113], v[112:113], v[118:119]
	v_mov_b32_e32 v117, v21
	v_mov_b32_e32 v121, v23
	s_waitcnt vmcnt(11)
	v_pk_mul_f32 v[118:119], v[66:67], v[66:67]
	v_pk_mul_f32 v[122:123], v[64:65], v[64:65]
	s_waitcnt vmcnt(10)
	v_pk_mul_f32 v[124:125], v[70:71], v[70:71]
	v_pk_mul_f32 v[126:127], v[68:69], v[68:69]
	s_waitcnt vmcnt(8)
	v_mul_f32_e32 v128, v77, v77
	v_mul_f32_e32 v130, v79, v79
	s_waitcnt vmcnt(7)
	v_pk_mul_f32 v[132:133], v[82:83], v[82:83]
	v_pk_mul_f32 v[134:135], v[80:81], v[80:81]
	s_waitcnt vmcnt(6)
	v_pk_mul_f32 v[136:137], v[86:87], v[86:87]
	v_pk_mul_f32 v[138:139], v[84:85], v[84:85]
	s_waitcnt vmcnt(5)
	v_pk_mul_f32 v[140:141], v[90:91], v[90:91]
	v_pk_mul_f32 v[142:143], v[88:89], v[88:89]
	s_waitcnt vmcnt(4)
	v_pk_mul_f32 v[144:145], v[94:95], v[94:95]
	v_pk_mul_f32 v[146:147], v[92:93], v[92:93]
	v_pk_add_f32 v[116:117], v[116:117], v[120:121]
	v_pk_mov_b32 v[120:121], v[122:123], v[118:119] op_sel:[1,0]
	v_mov_b32_e32 v123, v119
	v_pk_mov_b32 v[118:119], v[126:127], v[124:125] op_sel:[1,0]
	v_mov_b32_e32 v127, v125
	v_pk_fma_f32 v[124:125], v[76:77], v[76:77], v[128:129] op_sel_hi:[1,1,0]
	v_pk_fma_f32 v[128:129], v[78:79], v[78:79], v[130:131] op_sel_hi:[1,1,0]
	v_pk_mov_b32 v[130:131], v[134:135], v[132:133] op_sel:[1,0]
	v_mov_b32_e32 v135, v133
	v_pk_mov_b32 v[132:133], v[138:139], v[136:137] op_sel:[1,0]
	v_mov_b32_e32 v139, v137
	v_pk_mov_b32 v[136:137], v[142:143], v[140:141] op_sel:[1,0]
	v_mov_b32_e32 v143, v141
	v_pk_mov_b32 v[140:141], v[146:147], v[144:145] op_sel:[1,0]
	v_mov_b32_e32 v147, v145
	v_mul_f32_e32 v33, v56, v56
	v_mul_f32_e32 v155, v57, v57
	s_waitcnt vmcnt(3)
	v_mul_f32_e32 v148, v97, v97
	v_mul_f32_e32 v150, v99, v99
	s_waitcnt vmcnt(1)
	v_mul_f32_e32 v152, v105, v105
	v_mul_f32_e32 v154, v107, v107
	v_pk_add_f32 v[114:115], v[114:115], v[114:115] op_sel:[0,1] op_sel_hi:[1,0]
	v_pk_add_f32 v[112:113], v[112:113], v[112:113] op_sel:[0,1] op_sel_hi:[1,0]
	v_pk_add_f32 v[120:121], v[120:121], v[122:123]
	v_pk_add_f32 v[118:119], v[118:119], v[126:127]
	v_pk_add_f32 v[122:123], v[130:131], v[134:135]
	v_pk_add_f32 v[126:127], v[132:133], v[138:139]
	v_pk_add_f32 v[130:131], v[136:137], v[142:143]
	v_pk_add_f32 v[132:133], v[140:141], v[146:147]
	v_mul_f32_e32 v21, v74, v74
	v_mul_f32_e32 v23, v75, v75
	v_mul_f32_e32 v156, v72, v72
	v_mul_f32_e32 v157, v73, v73
	v_mul_f32_e32 v158, v102, v102
	v_mul_f32_e32 v159, v103, v103
	s_waitcnt vmcnt(0)
	v_mul_f32_e32 v160, v110, v110
	v_mul_f32_e32 v161, v111, v111
	v_mul_f32_e32 v162, v100, v100
	v_mul_f32_e32 v163, v101, v101
	v_mul_f32_e32 v164, v108, v108
	v_mul_f32_e32 v165, v109, v109
	v_pk_fma_f32 v[144:145], v[96:97], v[96:97], v[148:149] op_sel_hi:[1,1,0]
	v_pk_fma_f32 v[148:149], v[98:99], v[98:99], v[150:151] op_sel_hi:[1,1,0]
	v_pk_fma_f32 v[150:151], v[104:105], v[104:105], v[152:153] op_sel_hi:[1,1,0]
	v_pk_fma_f32 v[152:153], v[106:107], v[106:107], v[154:155] op_sel_hi:[1,1,0]
	v_mov_b32_e32 v115, v33
	v_mov_b32_e32 v113, v155
	v_pk_add_f32 v[120:121], v[120:121], v[120:121] op_sel:[0,1] op_sel_hi:[1,0]
	v_pk_add_f32 v[118:119], v[118:119], v[118:119] op_sel:[0,1] op_sel_hi:[1,0]
	v_pk_add_f32 v[122:123], v[122:123], v[122:123] op_sel:[0,1] op_sel_hi:[1,0]
	v_pk_add_f32 v[126:127], v[126:127], v[126:127] op_sel:[0,1] op_sel_hi:[1,0]
	v_pk_add_f32 v[130:131], v[130:131], v[130:131] op_sel:[0,1] op_sel_hi:[1,0]
	v_pk_add_f32 v[132:133], v[132:133], v[132:133] op_sel:[0,1] op_sel_hi:[1,0]
	v_mov_b32_e32 v125, v21
	v_mov_b32_e32 v129, v23
	v_mov_b32_e32 v145, v158
	v_mov_b32_e32 v149, v159
	v_mov_b32_e32 v151, v160
	v_mov_b32_e32 v153, v161
	v_pk_add_f32 v[112:113], v[114:115], v[112:113]
	v_mov_b32_e32 v121, v156
	v_mov_b32_e32 v119, v157
	v_mov_b32_e32 v123, v162
	v_mov_b32_e32 v127, v163
	v_mov_b32_e32 v131, v164
	v_mov_b32_e32 v133, v165
	v_pk_add_f32 v[114:115], v[124:125], v[128:129]
	v_pk_add_f32 v[124:125], v[144:145], v[148:149]
	v_pk_add_f32 v[128:129], v[150:151], v[152:153]
	v_pk_add_f32 v[112:113], v[112:113], v[116:117]
	v_pk_add_f32 v[116:117], v[120:121], v[118:119]
	v_pk_add_f32 v[120:121], v[122:123], v[126:127]
	v_pk_add_f32 v[122:123], v[130:131], v[132:133]
	v_pk_add_f32 v[114:115], v[116:117], v[114:115]
	v_pk_add_f32 v[116:117], v[120:121], v[124:125]
	v_pk_add_f32 v[120:121], v[122:123], v[128:129]
	v_mov_b32_e32 v119, v112
	v_mov_b32_e32 v118, v114
	v_mov_b32_e32 v112, v115
	v_mov_b32_e32 v114, v120
	v_mov_b32_e32 v115, v116
	v_mov_b32_e32 v116, v121
	v_pk_add_f32 v[112:113], v[118:119], v[112:113]
	v_pk_add_f32 v[114:115], v[114:115], v[116:117]
	ds_bpermute_b32 v117, v19, v113
	ds_bpermute_b32 v116, v19, v112
	ds_bpermute_b32 v119, v19, v115
	ds_bpermute_b32 v118, v19, v114
	s_waitcnt lgkmcnt(2)
	v_pk_add_f32 v[112:113], v[112:113], v[116:117]
	ds_bpermute_b32 v117, v43, v113
	s_waitcnt lgkmcnt(1)
	v_pk_add_f32 v[114:115], v[114:115], v[118:119]
	ds_bpermute_b32 v116, v43, v112
	ds_bpermute_b32 v119, v43, v115
	ds_bpermute_b32 v118, v43, v114
	s_waitcnt lgkmcnt(2)
	v_pk_add_f32 v[112:113], v[112:113], v[116:117]
	ds_bpermute_b32 v117, v44, v113
	s_waitcnt lgkmcnt(1)
	v_pk_add_f32 v[114:115], v[114:115], v[118:119]
	ds_bpermute_b32 v116, v44, v112
	ds_bpermute_b32 v119, v44, v115
	ds_bpermute_b32 v118, v44, v114
	s_waitcnt lgkmcnt(2)
	v_pk_add_f32 v[112:113], v[112:113], v[116:117]
	ds_bpermute_b32 v117, v45, v113
	s_waitcnt lgkmcnt(1)
	v_pk_add_f32 v[114:115], v[114:115], v[118:119]
	ds_bpermute_b32 v116, v45, v112
	ds_bpermute_b32 v119, v45, v115
	ds_bpermute_b32 v118, v45, v114
	s_waitcnt lgkmcnt(2)
	v_pk_add_f32 v[112:113], v[112:113], v[116:117]
	ds_bpermute_b32 v117, v46, v113
	s_waitcnt lgkmcnt(1)
	v_pk_add_f32 v[114:115], v[114:115], v[118:119]
	ds_bpermute_b32 v116, v46, v112
	ds_bpermute_b32 v119, v46, v115
	ds_bpermute_b32 v118, v46, v114
	s_waitcnt lgkmcnt(2)
	v_pk_add_f32 v[112:113], v[112:113], v[116:117]
	ds_bpermute_b32 v117, v47, v113
	s_waitcnt lgkmcnt(1)
	v_pk_add_f32 v[114:115], v[114:115], v[118:119]
	ds_bpermute_b32 v116, v47, v112
	ds_bpermute_b32 v119, v47, v115
	ds_bpermute_b32 v118, v47, v114
	s_waitcnt lgkmcnt(2)
	v_pk_add_f32 v[112:113], v[112:113], v[116:117]
	s_nop 0
	v_pk_fma_f32 v[112:113], v[112:113], s[12:13], v[30:31] op_sel_hi:[1,0,0]
	s_waitcnt lgkmcnt(0)
	v_pk_add_f32 v[114:115], v[114:115], v[118:119]
	v_mul_f32_e32 v21, 0x4b800000, v113
	v_pk_fma_f32 v[114:115], v[114:115], s[12:13], v[30:31] op_sel_hi:[1,0,0]
	v_mul_f32_e32 v23, 0x4b800000, v112
	v_cmp_gt_f32_e32 vcc, s15, v112
	v_mul_f32_e32 v33, 0x4b800000, v115
	v_cmp_gt_f32_e64 s[0:1], s15, v115
	v_mul_f32_e32 v116, 0x4b800000, v114
	v_cmp_gt_f32_e64 s[4:5], s15, v114
	v_cmp_gt_f32_e64 s[6:7], s15, v113
	v_cndmask_b32_e32 v23, v112, v23, vcc
	v_cndmask_b32_e64 v33, v115, v33, s[0:1]
	v_cndmask_b32_e64 v21, v113, v21, s[6:7]
	v_cndmask_b32_e64 v112, v114, v116, s[4:5]
	v_rsq_f32_e32 v21, v21
	v_rsq_f32_e32 v23, v23
	v_rsq_f32_e32 v33, v33
	v_rsq_f32_e32 v112, v112
	v_mul_f32_e32 v113, 0x45800000, v21
	v_mul_f32_e32 v114, 0x45800000, v23
	v_mul_f32_e32 v115, 0x45800000, v33
	v_mul_f32_e32 v116, 0x45800000, v112
	v_cndmask_b32_e64 v21, v21, v113, s[6:7]
	v_cndmask_b32_e32 v23, v23, v114, vcc
	v_cndmask_b32_e64 v33, v33, v115, s[0:1]
	v_cndmask_b32_e64 v112, v112, v116, s[4:5]
	v_mul_f32_e32 v48, v48, v21
	v_mul_f32_e32 v49, v49, v21
	v_mul_f32_e32 v50, v50, v21
	v_mul_f32_e32 v51, v51, v21
	v_mul_f32_e32 v52, v52, v21
	v_mul_f32_e32 v53, v53, v21
	v_mul_f32_e32 v54, v54, v21
	v_mul_f32_e32 v55, v55, v21
	v_mul_f32_e32 v60, v60, v21
	v_mul_f32_e32 v61, v61, v21
	v_mul_f32_e32 v62, v62, v21
	v_mul_f32_e32 v63, v63, v21
	v_mul_f32_e32 v56, v56, v21
	v_mul_f32_e32 v57, v57, v21
	v_mul_f32_e32 v58, v58, v21
	v_mul_f32_e32 v21, v59, v21
	v_mul_f32_e32 v59, v64, v23
	v_mul_f32_e32 v64, v65, v23
	v_mul_f32_e32 v65, v66, v23
	v_mul_f32_e32 v66, v67, v23
	v_mul_f32_e32 v67, v68, v23
	v_mul_f32_e32 v68, v69, v23
	v_mul_f32_e32 v69, v70, v23
	v_mul_f32_e32 v70, v71, v23
	v_mul_f32_e32 v71, v76, v23
	v_mul_f32_e32 v76, v77, v23
	v_mul_f32_e32 v77, v78, v23
	v_mul_f32_e32 v78, v79, v23
	v_mul_f32_e32 v72, v72, v23
	v_mul_f32_e32 v73, v73, v23
	v_mul_f32_e32 v74, v74, v23
	v_mul_f32_e32 v23, v75, v23
	v_mul_f32_e32 v75, v80, v33
	v_mul_f32_e32 v79, v81, v33
	v_mul_f32_e32 v80, v82, v33
	v_mul_f32_e32 v81, v83, v33
	v_mul_f32_e32 v82, v84, v33
	v_mul_f32_e32 v83, v85, v33
	v_mul_f32_e32 v84, v86, v33
	v_mul_f32_e32 v85, v87, v33
	v_mul_f32_e32 v86, v96, v33
	v_mul_f32_e32 v87, v97, v33
	v_mul_f32_e32 v96, v98, v33
	v_mul_f32_e32 v97, v99, v33
	v_mul_f32_e32 v98, v100, v33
	v_mul_f32_e32 v99, v101, v33
	v_mul_f32_e32 v100, v102, v33
	v_mul_f32_e32 v33, v103, v33
	v_mul_f32_e32 v88, v88, v112
	v_mul_f32_e32 v89, v89, v112
	v_mul_f32_e32 v90, v90, v112
	v_mul_f32_e32 v91, v91, v112
	v_mul_f32_e32 v92, v92, v112
	v_mul_f32_e32 v93, v93, v112
	v_mul_f32_e32 v94, v94, v112
	v_mul_f32_e32 v95, v95, v112
	v_mul_f32_e32 v101, v104, v112
	v_mul_f32_e32 v102, v105, v112
	v_mul_f32_e32 v103, v106, v112
	v_mul_f32_e32 v104, v107, v112
	v_mul_f32_e32 v105, v108, v112
	v_mul_f32_e32 v106, v109, v112
	v_mul_f32_e32 v107, v110, v112
	v_mul_f32_e32 v108, v111, v112
	v_mul_f32_e32 v48, v10, v48
	v_mul_f32_e32 v49, v11, v49
	v_mul_f32_e32 v50, v12, v50
	v_mul_f32_e32 v51, v13, v51
	v_mul_f32_e32 v59, v10, v59
	v_mul_f32_e32 v64, v11, v64
	v_mul_f32_e32 v65, v12, v65
	v_mul_f32_e32 v66, v13, v66
	v_mul_f32_e32 v75, v10, v75
	v_mul_f32_e32 v79, v11, v79
	v_mul_f32_e32 v80, v12, v80
	v_mul_f32_e32 v81, v13, v81
	v_mul_f32_e32 v88, v10, v88
	v_mul_f32_e32 v89, v11, v89
	v_mul_f32_e32 v90, v12, v90
	v_mul_f32_e32 v91, v13, v91
	v_mul_f32_e32 v10, v2, v52
	v_mul_f32_e32 v11, v3, v53
	v_mul_f32_e32 v12, v4, v54
	v_mul_f32_e32 v13, v5, v55
	v_mul_f32_e32 v52, v2, v67
	v_mul_f32_e32 v53, v3, v68
	v_mul_f32_e32 v54, v4, v69
	v_mul_f32_e32 v55, v5, v70
	v_mul_f32_e32 v67, v2, v82
	v_mul_f32_e32 v68, v3, v83
	v_mul_f32_e32 v69, v4, v84
	v_mul_f32_e32 v70, v5, v85
	v_mul_f32_e32 v82, v2, v92
	v_mul_f32_e32 v83, v3, v93
	v_mul_f32_e32 v84, v4, v94
	v_mul_f32_e32 v85, v5, v95
	v_mul_f32_e32 v60, v14, v60
	v_mul_f32_e32 v61, v15, v61
	v_mul_f32_e32 v62, v16, v62
	v_mul_f32_e32 v63, v17, v63
	v_mul_f32_e32 v71, v14, v71
	v_mul_f32_e32 v76, v15, v76
	v_mul_f32_e32 v77, v16, v77
	v_mul_f32_e32 v78, v17, v78
	v_mul_f32_e32 v86, v14, v86
	v_mul_f32_e32 v87, v15, v87
	v_mul_f32_e32 v92, v16, v96
	v_mul_f32_e32 v93, v17, v97
	v_mul_f32_e32 v94, v14, v101
	v_mul_f32_e32 v95, v15, v102
	v_mul_f32_e32 v96, v16, v103
	v_mul_f32_e32 v97, v17, v104
	v_mul_f32_e32 v14, v6, v56
	v_mul_f32_e32 v15, v7, v57
	v_mul_f32_e32 v16, v8, v58
	v_mul_f32_e32 v17, v9, v21
	v_mul_f32_e32 v56, v7, v73
	v_mul_f32_e32 v57, v8, v74
	v_mul_f32_e32 v58, v6, v98
	v_cvt_pk_bf16_f32 v2, v48, v49
	v_cvt_pk_bf16_f32 v3, v50, v51
	v_mul_f32_e32 v21, v6, v72
	v_mul_f32_e32 v23, v9, v23
	v_mul_f32_e32 v72, v7, v99
	v_mul_f32_e32 v73, v8, v100
	v_mul_f32_e32 v33, v9, v33
	v_mul_f32_e32 v74, v6, v105
	v_mul_f32_e32 v98, v7, v106
	v_mul_f32_e32 v99, v8, v107
	v_mul_f32_e32 v100, v9, v108
	v_cvt_pk_bf16_f32 v4, v10, v11
	v_cvt_pk_bf16_f32 v5, v12, v13
	v_cvt_pk_bf16_f32 v6, v60, v61
	v_cvt_pk_bf16_f32 v7, v62, v63
	v_cvt_pk_bf16_f32 v8, v14, v15
	v_cvt_pk_bf16_f32 v9, v16, v17
	v_cvt_pk_bf16_f32 v10, v59, v64
	v_cvt_pk_bf16_f32 v11, v65, v66
	v_cvt_pk_bf16_f32 v12, v52, v53
	v_cvt_pk_bf16_f32 v13, v54, v55
	v_cvt_pk_bf16_f32 v14, v71, v76
	v_cvt_pk_bf16_f32 v15, v77, v78
	v_cvt_pk_bf16_f32 v16, v21, v56
	v_cvt_pk_bf16_f32 v17, v57, v23
	v_cvt_pk_bf16_f32 v48, v75, v79
	v_cvt_pk_bf16_f32 v49, v80, v81
	v_cvt_pk_bf16_f32 v50, v67, v68
	v_cvt_pk_bf16_f32 v51, v69, v70
	v_cvt_pk_bf16_f32 v52, v86, v87
	v_cvt_pk_bf16_f32 v53, v92, v93
	v_cvt_pk_bf16_f32 v54, v58, v72
	v_cvt_pk_bf16_f32 v55, v73, v33
	v_cvt_pk_bf16_f32 v56, v88, v89
	v_cvt_pk_bf16_f32 v57, v90, v91
	v_cvt_pk_bf16_f32 v58, v82, v83
	v_cvt_pk_bf16_f32 v59, v84, v85
	v_cvt_pk_bf16_f32 v60, v94, v95
	v_cvt_pk_bf16_f32 v61, v96, v97
	v_cvt_pk_bf16_f32 v62, v74, v98
	v_cvt_pk_bf16_f32 v63, v99, v100
	global_store_dwordx2 v[34:35], v[2:3], off sc1
	global_store_dwordx2 v[34:35], v[4:5], off offset:512 sc1
	global_store_dwordx2 v[34:35], v[6:7], off offset:1024 sc1
	global_store_dwordx2 v[34:35], v[8:9], off offset:1536 sc1
	global_store_dwordx2 v[40:41], v[10:11], off sc1
	global_store_dwordx2 v[40:41], v[12:13], off offset:512 sc1
	global_store_dwordx2 v[40:41], v[14:15], off offset:1024 sc1
	global_store_dwordx2 v[40:41], v[16:17], off offset:1536 sc1
	global_store_dwordx2 v[38:39], v[48:49], off sc1
	global_store_dwordx2 v[38:39], v[50:51], off offset:512 sc1
	global_store_dwordx2 v[38:39], v[52:53], off offset:1024 sc1
	global_store_dwordx2 v[38:39], v[54:55], off offset:1536 sc1
	global_store_dwordx2 v[36:37], v[56:57], off sc1
	global_store_dwordx2 v[36:37], v[58:59], off offset:512 sc1
	global_store_dwordx2 v[36:37], v[60:61], off offset:1024 sc1
	global_store_dwordx2 v[36:37], v[62:63], off offset:1536 sc1
	s_andn2_b64 exec, exec, s[10:11]
	s_cbranch_execnz .LBB0_24

.LBB0_27:
	global_load_dwordx4 v[20:23], v[6:7], off nt
	global_load_dwordx4 v[24:27], v[6:7], off offset:1024 nt
	global_load_dwordx4 v[28:31], v[6:7], off offset:2048 nt
	global_load_dwordx4 v[32:35], v[6:7], off offset:3072 nt
	global_load_dwordx4 v[36:39], v[4:5], off
	global_load_dwordx4 v[44:47], v[4:5], off offset:1024
	global_load_dwordx4 v[48:51], v[4:5], off offset:2048
	global_load_dwordx4 v[52:55], v[4:5], off offset:3072
	v_add_u32_e32 v16, 0x8000, v18
	v_add_u32_e32 v18, s2, v18
	v_cmp_lt_i32_e32 vcc, s8, v18
	s_or_b64 s[6:7], vcc, s[6:7]
	v_ashrrev_i32_e32 v17, 31, v16
	v_lshlrev_b64 v[16:17], 11, v[16:17]
	v_lshl_add_u64 v[6:7], v[6:7], 0, s[4:5]
	v_lshl_add_u64 v[16:17], v[2:3], 0, v[16:17]
	s_waitcnt vmcnt(7)
	v_pk_mul_f32 v[40:41], v[22:23], v[22:23]
	v_pk_mul_f32 v[56:57], v[20:21], v[20:21]
	s_waitcnt vmcnt(6)
	v_pk_mul_f32 v[58:59], v[26:27], v[26:27]
	v_pk_mul_f32 v[60:61], v[24:25], v[24:25]
	v_pk_mov_b32 v[66:67], v[56:57], v[40:41] op_sel:[1,0]
	v_mov_b32_e32 v57, v41
	v_pk_mov_b32 v[40:41], v[60:61], v[58:59] op_sel:[1,0]
	v_mov_b32_e32 v61, v59
	s_waitcnt vmcnt(4)
	v_mul_f32_e32 v65, v35, v35
	v_mul_f32_e32 v62, v29, v29
	v_mul_f32_e32 v64, v31, v31
	v_pk_add_f32 v[56:57], v[66:67], v[56:57]
	v_pk_add_f32 v[40:41], v[40:41], v[60:61]
	v_mul_f32_e32 v15, v32, v32
	v_mul_f32_e32 v19, v33, v33
	v_mul_f32_e32 v43, v34, v34
	v_pk_fma_f32 v[58:59], v[28:29], v[28:29], v[62:63] op_sel_hi:[1,1,0]
	v_pk_fma_f32 v[62:63], v[30:31], v[30:31], v[64:65] op_sel_hi:[1,1,0]
	v_pk_add_f32 v[56:57], v[56:57], v[56:57] op_sel:[0,1] op_sel_hi:[1,0]
	v_pk_add_f32 v[40:41], v[40:41], v[40:41] op_sel:[0,1] op_sel_hi:[1,0]
	v_mov_b32_e32 v59, v43
	v_mov_b32_e32 v63, v65
	v_mov_b32_e32 v57, v15
	v_mov_b32_e32 v41, v19
	v_pk_add_f32 v[58:59], v[58:59], v[62:63]
	v_pk_add_f32 v[40:41], v[56:57], v[40:41]
	s_nop 0
	v_pk_add_f32 v[40:41], v[40:41], v[58:59]
	s_nop 0
	v_add_f32_e32 v15, v40, v41
	ds_bpermute_b32 v19, v8, v15
	s_waitcnt lgkmcnt(0)
	v_add_f32_e32 v15, v15, v19
	ds_bpermute_b32 v19, v9, v15
	s_waitcnt lgkmcnt(0)
	v_add_f32_e32 v15, v15, v19
	ds_bpermute_b32 v19, v10, v15
	s_waitcnt lgkmcnt(0)
	v_add_f32_e32 v15, v15, v19
	ds_bpermute_b32 v19, v11, v15
	s_waitcnt lgkmcnt(0)
	v_add_f32_e32 v15, v15, v19
	ds_bpermute_b32 v19, v12, v15
	s_waitcnt lgkmcnt(0)
	v_add_f32_e32 v15, v15, v19
	ds_bpermute_b32 v19, v13, v15
	s_waitcnt lgkmcnt(0)
	v_add_f32_e32 v15, v15, v19
	v_fmamk_f32 v15, v15, 0x3a800000, v14
	v_mul_f32_e32 v19, 0x4b800000, v15
	v_cmp_gt_f32_e32 vcc, s3, v15
	s_nop 1
	v_cndmask_b32_e32 v15, v15, v19, vcc
	v_rsq_f32_e32 v15, v15
	s_nop 0
	v_mul_f32_e32 v19, 0x45800000, v15
	v_cndmask_b32_e32 v15, v15, v19, vcc
	v_mul_f32_e32 v19, v20, v15
	v_mul_f32_e32 v20, v21, v15
	v_mul_f32_e32 v21, v22, v15
	v_mul_f32_e32 v22, v23, v15
	v_mul_f32_e32 v23, v24, v15
	v_mul_f32_e32 v24, v25, v15
	v_mul_f32_e32 v25, v26, v15
	v_mul_f32_e32 v26, v27, v15
	v_mul_f32_e32 v27, v28, v15
	s_waitcnt vmcnt(3)
	v_mul_f32_e32 v20, v37, v20
	v_mul_f32_e32 v21, v38, v21
	v_mul_f32_e32 v28, v29, v15
	v_mul_f32_e32 v29, v30, v15
	v_mul_f32_e32 v30, v31, v15
	v_mul_f32_e32 v31, v32, v15
	v_mul_f32_e32 v32, v33, v15
	v_mul_f32_e32 v33, v34, v15
	v_mul_f32_e32 v15, v35, v15
	v_mul_f32_e32 v19, v36, v19
	v_mul_f32_e32 v22, v39, v22
	s_waitcnt vmcnt(2)
	v_mul_f32_e32 v23, v44, v23
	v_mul_f32_e32 v24, v45, v24
	v_mul_f32_e32 v25, v46, v25
	v_mul_f32_e32 v26, v47, v26
	s_waitcnt vmcnt(1)
	v_mul_f32_e32 v27, v48, v27
	v_cvt_pk_bf16_f32 v20, v19, v20
	v_cvt_pk_bf16_f32 v21, v21, v22
	v_mul_f32_e32 v28, v49, v28
	v_mul_f32_e32 v29, v50, v29
	v_mul_f32_e32 v30, v51, v30
	s_waitcnt vmcnt(0)
	v_mul_f32_e32 v31, v52, v31
	v_mul_f32_e32 v32, v53, v32
	v_mul_f32_e32 v33, v54, v33
	v_mul_f32_e32 v15, v55, v15
	v_cvt_pk_bf16_f32 v22, v23, v24
	v_cvt_pk_bf16_f32 v23, v25, v26
	v_cvt_pk_bf16_f32 v24, v27, v28
	v_cvt_pk_bf16_f32 v25, v29, v30
	v_cvt_pk_bf16_f32 v26, v31, v32
	v_cvt_pk_bf16_f32 v27, v33, v15
	global_store_dwordx2 v[16:17], v[20:21], off sc1
	global_store_dwordx2 v[16:17], v[22:23], off offset:512 sc1
	global_store_dwordx2 v[16:17], v[24:25], off offset:1024 sc1
	global_store_dwordx2 v[16:17], v[26:27], off offset:1536 sc1
	s_andn2_b64 exec, exec, s[6:7]
	s_cbranch_execnz .LBB0_27

.LBB0_30:
	v_bfe_u32 v6, v12, 6, 6
	v_and_b32_e32 v13, 0xfc0, v3
	v_and_b32_e32 v16, 0x7000, v12
	v_cmp_gt_u32_e32 vcc, s8, v12
	v_or3_b32 v6, v13, v16, v6
	v_lshlrev_b32_e32 v6, 2, v6
	v_cndmask_b32_e32 v15, v8, v9, vcc
	v_cndmask_b32_e32 v14, v10, v11, vcc
	v_lshl_add_u64 v[14:15], v[14:15], 0, v[6:7]
	v_add_u32_e32 v12, s2, v12
	global_load_dword v6, v[14:15], off
	v_cmp_lt_i32_e32 vcc, s9, v12
	v_add_u32_e32 v3, s3, v3
	s_or_b64 s[6:7], vcc, s[6:7]
	s_waitcnt vmcnt(0)
	v_cvt_pk_bf16_f32 v6, v6, v7
	global_store_short v[4:5], v6, off sc1
	v_lshl_add_u64 v[4:5], v[4:5], 0, s[4:5]
	s_andn2_b64 exec, exec, s[6:7]
	s_cbranch_execnz .LBB0_30

.LBB0_34:
	s_or_b64 exec, exec, s[34:35]
	v_lshl_or_b32 v4, v11, 4, v3
	v_ashrrev_i32_e32 v5, 31, v4
	v_add_u32_e32 v2, s2, v2
	v_cvt_f32_f64_e32 v6, v[6:7]
	v_lshl_add_u64 v[4:5], v[4:5], 2, s[86:87]
	v_cmp_lt_i32_e32 vcc, s3, v2
	global_store_dword v[4:5], v6, off sc1
	v_cvt_f32_f64_e32 v6, v[8:9]
	s_or_b64 s[0:1], vcc, s[0:1]
	global_store_dword v[4:5], v6, off offset:32 sc1
	s_andn2_b64 exec, exec, s[0:1]
	s_cbranch_execz .LBB0_42
